# nt also on the short-conv phase loads/stores and the w_in_1 conversion stores (LN + prologue nt kept)
# speedup vs baseline: 1.0092x; 1.0017x over previous
.LBB0_323:
	s_ashr_i32 s8, s3, 31
	s_lshr_b32 s8, s8, 23
	s_add_i32 s8, s3, s8
	s_ashr_i32 s9, s8, 9
	s_lshl_b32 s8, s9, 6
	v_or_b32_e32 v16, s8, v1
	s_lshl_b32 s9, s9, 14
	v_ashrrev_i32_e32 v17, 31, v16
	s_sub_i32 s10, s13, s9
	v_lshlrev_b64 v[16:17], 16, v[16:17]
	s_ashr_i32 s11, s10, 31
	v_lshl_add_u64 v[16:17], s[4:5], 0, v[16:17]
	v_lshl_add_u64 v[16:17], s[10:11], 2, v[16:17]
	v_lshl_add_u64 v[16:17], v[16:17], 0, v[2:3]
	v_add_co_u32_e32 v18, vcc, s15, v16
	s_ashr_i32 s9, s8, 31
	s_nop 0
	v_addc_co_u32_e32 v19, vcc, 0, v17, vcc
	v_add_co_u32_e32 v20, vcc, s16, v16
	s_lshl_b64 s[8:9], s[8:9], 1
	s_nop 0
	v_addc_co_u32_e32 v21, vcc, 0, v17, vcc
	v_add_co_u32_e32 v22, vcc, s17, v16
	s_add_i32 s3, s3, s12
	s_nop 0
	v_addc_co_u32_e32 v23, vcc, 0, v17, vcc
	v_add_co_u32_e32 v24, vcc, s18, v16
	s_add_i32 s13, s13, s14
	s_nop 0
	v_addc_co_u32_e32 v25, vcc, 0, v17, vcc
	v_add_co_u32_e32 v26, vcc, s19, v16
	s_cmpk_gt_i32 s3, 0x7fff
	s_nop 0
	v_addc_co_u32_e32 v27, vcc, 0, v17, vcc
	v_add_co_u32_e32 v28, vcc, s24, v16
	s_nop 1
	v_addc_co_u32_e32 v29, vcc, 0, v17, vcc
	v_add_co_u32_e32 v30, vcc, s25, v16
	s_nop 1
	v_addc_co_u32_e32 v31, vcc, 0, v17, vcc
	v_add_co_u32_e32 v32, vcc, s26, v16
	s_nop 1
	v_addc_co_u32_e32 v33, vcc, 0, v17, vcc
	v_add_co_u32_e32 v34, vcc, s27, v16
	s_nop 1
	v_addc_co_u32_e32 v35, vcc, 0, v17, vcc
	v_add_co_u32_e32 v36, vcc, s30, v16
	s_nop 1
	v_addc_co_u32_e32 v37, vcc, 0, v17, vcc
	v_add_co_u32_e32 v38, vcc, s31, v16
	s_nop 1
	v_addc_co_u32_e32 v39, vcc, 0, v17, vcc
	v_add_co_u32_e32 v40, vcc, s34, v16
	s_nop 1
	v_addc_co_u32_e32 v41, vcc, 0, v17, vcc
	v_add_co_u32_e32 v42, vcc, s35, v16
	s_nop 1
	v_addc_co_u32_e32 v43, vcc, 0, v17, vcc
	v_add_co_u32_e32 v44, vcc, s36, v16
	s_nop 1
	v_addc_co_u32_e32 v45, vcc, 0, v17, vcc
	v_add_co_u32_e32 v46, vcc, s37, v16
	s_nop 1
	v_addc_co_u32_e32 v47, vcc, 0, v17, vcc
	v_add_co_u32_e32 v48, vcc, s38, v16
	s_nop 1
	v_addc_co_u32_e32 v49, vcc, 0, v17, vcc
	v_add_co_u32_e32 v50, vcc, s39, v16
	s_nop 1
	v_addc_co_u32_e32 v51, vcc, 0, v17, vcc
	v_add_co_u32_e32 v52, vcc, s40, v16
	s_nop 1
	v_addc_co_u32_e32 v53, vcc, 0, v17, vcc
	v_add_co_u32_e32 v54, vcc, s41, v16
	s_nop 1
	v_addc_co_u32_e32 v55, vcc, 0, v17, vcc
	v_add_co_u32_e32 v56, vcc, s42, v16
	s_nop 1
	v_addc_co_u32_e32 v57, vcc, 0, v17, vcc
	v_add_co_u32_e32 v58, vcc, s43, v16
	s_nop 1
	v_addc_co_u32_e32 v59, vcc, 0, v17, vcc
	v_add_co_u32_e32 v60, vcc, s44, v16
	s_nop 1
	v_addc_co_u32_e32 v61, vcc, 0, v17, vcc
	v_add_co_u32_e32 v62, vcc, s45, v16
	s_nop 1
	v_addc_co_u32_e32 v63, vcc, 0, v17, vcc
	v_add_co_u32_e32 v64, vcc, s46, v16
	s_nop 1
	v_addc_co_u32_e32 v65, vcc, 0, v17, vcc
	v_add_co_u32_e32 v66, vcc, s47, v16
	s_nop 1
	v_addc_co_u32_e32 v67, vcc, 0, v17, vcc
	v_add_co_u32_e32 v68, vcc, s48, v16
	s_nop 1
	v_addc_co_u32_e32 v69, vcc, 0, v17, vcc
	v_add_co_u32_e32 v70, vcc, s49, v16
	s_nop 1
	v_addc_co_u32_e32 v71, vcc, 0, v17, vcc
	v_add_co_u32_e32 v72, vcc, s50, v16
	s_nop 1
	v_addc_co_u32_e32 v73, vcc, 0, v17, vcc
	v_add_co_u32_e32 v74, vcc, s51, v16
	s_nop 1
	v_addc_co_u32_e32 v75, vcc, 0, v17, vcc
	v_add_co_u32_e32 v76, vcc, s52, v16
	s_nop 1
	v_addc_co_u32_e32 v77, vcc, 0, v17, vcc
	v_add_co_u32_e32 v78, vcc, s53, v16
	s_nop 1
	v_addc_co_u32_e32 v79, vcc, 0, v17, vcc
	global_load_dword v80, v[16:17], off nt
	global_load_dword v81, v[18:19], off nt
	global_load_dword v82, v[20:21], off nt
	global_load_dword v83, v[22:23], off nt
	global_load_dword v84, v[24:25], off nt
	global_load_dword v85, v[26:27], off nt
	s_nop 0
	global_load_dword v28, v[28:29], off nt
	s_nop 0
	global_load_dword v29, v[30:31], off nt
	s_nop 0
	global_load_dword v30, v[32:33], off nt
	global_load_dword v31, v[34:35], off nt
	s_nop 0
	global_load_dword v32, v[36:37], off nt
	global_load_dword v33, v[38:39], off nt
	global_load_dword v34, v[40:41], off nt
	global_load_dword v35, v[42:43], off nt
	s_nop 0
	global_load_dword v36, v[44:45], off nt
	global_load_dword v37, v[46:47], off nt
	global_load_dword v38, v[48:49], off nt
	global_load_dword v39, v[50:51], off nt
	global_load_dword v40, v[52:53], off nt
	global_load_dword v41, v[54:55], off nt
	global_load_dword v42, v[56:57], off nt
	global_load_dword v43, v[58:59], off nt
	global_load_dword v44, v[60:61], off nt
	global_load_dword v45, v[62:63], off nt
	global_load_dword v46, v[64:65], off nt
	global_load_dword v47, v[66:67], off nt
	global_load_dword v48, v[68:69], off nt
	global_load_dword v49, v[70:71], off nt
	global_load_dword v50, v[72:73], off nt
	global_load_dword v51, v[74:75], off nt
	global_load_dword v52, v[76:77], off nt
	global_load_dword v53, v[78:79], off nt
	v_add_u32_e32 v20, s10, v6
	v_add_u32_e32 v16, 8, v20
	v_add_u32_e32 v18, 16, v20
	v_ashrrev_i32_e32 v17, 31, v16
	v_ashrrev_i32_e32 v19, 31, v18
	v_lshlrev_b64 v[16:17], 13, v[16:17]
	s_waitcnt vmcnt(0)
	ds_write2_b32 v8, v80, v81 offset1:66
	ds_write2_b32 v8, v82, v83 offset0:132 offset1:198
	ds_write2_b32 v9, v84, v85 offset0:8 offset1:74
	ds_write2_b32 v9, v28, v29 offset0:140 offset1:206
	ds_write2_b32 v10, v30, v31 offset0:16 offset1:82
	ds_write2_b32 v10, v32, v33 offset0:148 offset1:214
	ds_write2_b32 v11, v34, v35 offset0:24 offset1:90
	ds_write2_b32 v11, v36, v37 offset0:156 offset1:222
	ds_write2_b32 v12, v38, v39 offset0:32 offset1:98
	ds_write2_b32 v12, v40, v41 offset0:164 offset1:230
	ds_write2_b32 v13, v42, v43 offset0:40 offset1:106
	ds_write2_b32 v13, v44, v45 offset0:172 offset1:238
	ds_write2_b32 v14, v46, v47 offset0:48 offset1:114
	ds_write2_b32 v14, v48, v49 offset0:180 offset1:246
	ds_write2_b32 v15, v50, v51 offset0:56 offset1:122
	ds_write2_b32 v15, v52, v53 offset0:188 offset1:254
	v_lshlrev_b64 v[18:19], 13, v[18:19]
	v_lshl_add_u64 v[16:17], s[6:7], 0, v[16:17]
	s_waitcnt lgkmcnt(0)
	v_ashrrev_i32_e32 v21, 31, v20
	v_lshl_add_u64 v[18:19], s[6:7], 0, v[18:19]
	v_lshl_add_u64 v[16:17], v[16:17], 0, s[8:9]
	v_lshlrev_b64 v[22:23], 13, v[20:21]
	v_lshl_add_u64 v[18:19], v[18:19], 0, s[8:9]
	v_lshl_add_u64 v[24:25], v[16:17], 0, v[4:5]
	ds_read2_b32 v[16:17], v7 offset1:33
	v_lshl_add_u64 v[22:23], s[6:7], 0, v[22:23]
	v_lshl_add_u64 v[26:27], v[18:19], 0, v[4:5]
	s_waitcnt lgkmcnt(0)
	v_cvt_pk_bf16_f32 v16, v16, v17
	ds_read2_b32 v[18:19], v7 offset0:66 offset1:99
	v_lshl_add_u64 v[22:23], v[22:23], 0, s[8:9]
	s_waitcnt lgkmcnt(0)
	v_cvt_pk_bf16_f32 v17, v18, v19
	ds_read2_b32 v[18:19], v7 offset0:132 offset1:165
	v_lshl_add_u64 v[22:23], v[22:23], 0, v[4:5]
	s_waitcnt lgkmcnt(0)
	v_cvt_pk_bf16_f32 v18, v18, v19
	ds_read2_b32 v[28:29], v7 offset0:198 offset1:231
	s_waitcnt lgkmcnt(0)
	v_cvt_pk_bf16_f32 v19, v28, v29
	ds_read2_b32 v[28:29], v7 offset0:8 offset1:41
	global_store_dwordx4 v[22:23], v[16:19], off nt
	v_add_u32_e32 v20, 24, v20
	v_ashrrev_i32_e32 v21, 31, v20
	s_waitcnt lgkmcnt(0)
	v_cvt_pk_bf16_f32 v16, v28, v29
	ds_read2_b32 v[18:19], v7 offset0:74 offset1:107
	s_waitcnt lgkmcnt(0)
	v_cvt_pk_bf16_f32 v17, v18, v19
	ds_read2_b32 v[18:19], v7 offset0:140 offset1:173
	s_waitcnt lgkmcnt(0)
	v_cvt_pk_bf16_f32 v18, v18, v19
	ds_read2_b32 v[22:23], v7 offset0:206 offset1:239
	s_waitcnt lgkmcnt(0)
	v_cvt_pk_bf16_f32 v19, v22, v23
	ds_read2_b32 v[22:23], v7 offset0:16 offset1:49
	global_store_dwordx4 v[24:25], v[16:19], off nt
	v_lshlrev_b64 v[20:21], 13, v[20:21]
	v_lshl_add_u64 v[20:21], s[6:7], 0, v[20:21]
	s_waitcnt lgkmcnt(0)
	v_cvt_pk_bf16_f32 v16, v22, v23
	ds_read2_b32 v[18:19], v7 offset0:82 offset1:115
	s_waitcnt lgkmcnt(0)
	v_cvt_pk_bf16_f32 v17, v18, v19
	ds_read2_b32 v[18:19], v7 offset0:148 offset1:181
	s_waitcnt lgkmcnt(0)
	v_cvt_pk_bf16_f32 v18, v18, v19
	ds_read2_b32 v[22:23], v7 offset0:214 offset1:247
	s_waitcnt lgkmcnt(0)
	v_cvt_pk_bf16_f32 v19, v22, v23
	ds_read2_b32 v[22:23], v7 offset0:24 offset1:57
	global_store_dwordx4 v[26:27], v[16:19], off nt
	v_lshl_add_u64 v[20:21], v[20:21], 0, s[8:9]
	v_lshl_add_u64 v[20:21], v[20:21], 0, v[4:5]
	s_waitcnt lgkmcnt(0)
	v_cvt_pk_bf16_f32 v16, v22, v23
	ds_read2_b32 v[18:19], v7 offset0:90 offset1:123
	s_waitcnt lgkmcnt(0)
	v_cvt_pk_bf16_f32 v17, v18, v19
	ds_read2_b32 v[18:19], v7 offset0:156 offset1:189
	s_waitcnt lgkmcnt(0)
	v_cvt_pk_bf16_f32 v18, v18, v19
	ds_read2_b32 v[22:23], v7 offset0:222 offset1:255
	s_waitcnt lgkmcnt(0)
	v_cvt_pk_bf16_f32 v19, v22, v23
	global_store_dwordx4 v[20:21], v[16:19], off nt
	s_waitcnt lgkmcnt(0)
	s_cbranch_scc0 .LBB0_323
	v_readlane_b32 s80, v255, 5

.LBB0_443:
	v_lshl_add_u32 v54, s6, 5, v1
	v_and_b32_e32 v30, 0x7f0, v54
	v_cmp_ne_u32_e32 vcc, 0, v30
	v_mov_b32_e32 v42, 0
	v_mov_b32_e32 v46, 0
	v_mov_b32_e32 v38, 0
	v_mov_b32_e32 v48, 0
	v_mov_b32_e32 v44, 0
	v_mov_b32_e32 v50, 0
	v_mov_b32_e32 v40, 0
	v_mov_b32_e32 v52, 0
	v_mov_b32_e32 v32, 0
	v_mov_b32_e32 v33, 0
	v_mov_b32_e32 v30, 0
	v_mov_b32_e32 v31, 0
	v_mov_b32_e32 v36, 0
	v_mov_b32_e32 v37, 0
	v_mov_b32_e32 v34, 0
	v_mov_b32_e32 v35, 0
	s_and_saveexec_b64 s[4:5], vcc
	s_cbranch_execz .LBB0_445
	v_ashrrev_i32_e32 v55, 31, v54
	v_lshlrev_b64 v[30:31], 15, v[54:55]
	v_lshl_add_u64 v[42:43], v[18:19], 0, v[30:31]
	v_add_co_u32_e32 v30, vcc, 0xffff0000, v42
	s_nop 1
	v_addc_co_u32_e32 v31, vcc, -1, v43, vcc
	v_add_co_u32_e32 v34, vcc, 0xffff2000, v42
	global_load_dwordx4 v[30:33], v[30:31], off nt
	s_nop 0
	v_addc_co_u32_e32 v35, vcc, -1, v43, vcc
	v_add_co_u32_e32 v38, vcc, 0xffff8000, v42
	global_load_dwordx4 v[34:37], v[34:35], off nt
	s_nop 0
	v_addc_co_u32_e32 v39, vcc, -1, v43, vcc
	v_add_co_u32_e32 v42, vcc, 0xffffa000, v42
	global_load_dwordx4 v[38:41], v[38:39], off nt
	s_nop 0
	v_addc_co_u32_e32 v43, vcc, -1, v43, vcc
	global_load_dwordx4 v[42:45], v[42:43], off nt
	s_waitcnt vmcnt(3)
	v_lshlrev_b32_e32 v46, 16, v30
	v_and_b32_e32 v47, 0xffff0000, v30
	v_lshlrev_b32_e32 v48, 16, v32
	v_and_b32_e32 v49, 0xffff0000, v32
	v_lshlrev_b32_e32 v32, 16, v33
	v_and_b32_e32 v33, 0xffff0000, v33
	s_waitcnt vmcnt(2)
	v_lshlrev_b32_e32 v50, 16, v34
	v_and_b32_e32 v51, 0xffff0000, v34
	v_lshlrev_b32_e32 v52, 16, v35
	v_and_b32_e32 v53, 0xffff0000, v35
	v_lshlrev_b32_e32 v54, 16, v36
	v_and_b32_e32 v55, 0xffff0000, v36
	v_lshlrev_b32_e32 v34, 16, v37
	v_and_b32_e32 v35, 0xffff0000, v37
	s_waitcnt vmcnt(1)
	v_lshlrev_b32_e32 v56, 16, v38
	v_and_b32_e32 v57, 0xffff0000, v38
	v_lshlrev_b32_e32 v38, 16, v39
	v_and_b32_e32 v39, 0xffff0000, v39
	v_lshlrev_b32_e32 v58, 16, v40
	v_and_b32_e32 v59, 0xffff0000, v40
	v_pk_mul_f32 v[34:35], v[32:33], v[34:35]
	v_pk_mul_f32 v[36:37], v[48:49], v[54:55]
	v_pk_mul_f32 v[32:33], v[46:47], v[50:51]
	v_lshlrev_b32_e32 v40, 16, v41
	v_and_b32_e32 v41, 0xffff0000, v41
	s_waitcnt vmcnt(0)
	v_lshlrev_b32_e32 v46, 16, v42
	v_and_b32_e32 v47, 0xffff0000, v42
	v_lshlrev_b32_e32 v42, 16, v43
	v_and_b32_e32 v43, 0xffff0000, v43
	v_lshlrev_b32_e32 v48, 16, v44
	v_and_b32_e32 v49, 0xffff0000, v44
	v_lshlrev_b32_e32 v44, 16, v45
	v_and_b32_e32 v45, 0xffff0000, v45
	v_lshlrev_b32_e32 v30, 16, v31
	v_and_b32_e32 v31, 0xffff0000, v31
	v_pk_mul_f32 v[40:41], v[40:41], v[44:45]
	v_pk_mul_f32 v[38:39], v[38:39], v[42:43]
	v_pk_mul_f32 v[44:45], v[58:59], v[48:49]
	v_pk_mul_f32 v[42:43], v[56:57], v[46:47]
	v_pk_mul_f32 v[30:31], v[30:31], v[52:53]
	v_mov_b32_e32 v46, v43
	v_mov_b32_e32 v48, v39
	v_mov_b32_e32 v50, v45
	v_mov_b32_e32 v52, v41

.LBB0_446:
	v_add_u32_e32 v54, s4, v88
	v_ashrrev_i32_e32 v55, 31, v54
	v_lshlrev_b64 v[62:63], 15, v[54:55]
	v_lshl_add_u64 v[62:63], v[18:19], 0, v[62:63]
	v_add_u32_e32 v56, 1, v54
	v_add_u32_e32 v58, 2, v54
	v_add_u32_e32 v60, 3, v54
	v_add_co_u32_e32 v84, vcc, s7, v62
	v_lshlrev_b64 v[54:55], 12, v[54:55]
	v_ashrrev_i32_e32 v57, 31, v56
	v_ashrrev_i32_e32 v59, 31, v58
	v_ashrrev_i32_e32 v61, 31, v60
	v_addc_co_u32_e32 v85, vcc, 0, v63, vcc
	v_lshl_add_u64 v[90:91], v[20:21], 0, v[54:55]
	v_lshlrev_b64 v[54:55], 15, v[56:57]
	v_lshlrev_b64 v[56:57], 12, v[56:57]
	v_lshlrev_b64 v[68:69], 15, v[58:59]
	v_lshlrev_b64 v[70:71], 15, v[60:61]
	global_load_dwordx4 v[64:67], v[62:63], off nt
	v_add_co_u32_e32 v62, vcc, s9, v62
	v_lshl_add_u64 v[82:83], v[20:21], 0, v[56:57]
	s_nop 0
	v_addc_co_u32_e32 v63, vcc, 0, v63, vcc
	v_lshl_add_u64 v[80:81], v[18:19], 0, v[68:69]
	v_lshl_add_u64 v[56:57], v[18:19], 0, v[70:71]
	global_load_dwordx4 v[68:71], v[84:85], off nt
	global_load_dwordx4 v[72:75], v[62:63], off nt
	global_load_dwordx4 v[76:79], v[84:85], off offset:-4096 nt
	v_lshl_add_u64 v[92:93], v[18:19], 0, v[54:55]
	v_add_co_u32_e32 v94, vcc, s7, v92
	v_lshlrev_b64 v[60:61], 12, v[60:61]
	s_nop 0
	v_addc_co_u32_e32 v95, vcc, 0, v93, vcc
	v_add_co_u32_e32 v96, vcc, s9, v92
	v_lshlrev_b64 v[58:59], 12, v[58:59]
	s_nop 0
	v_addc_co_u32_e32 v97, vcc, 0, v93, vcc
	v_add_co_u32_e32 v86, vcc, s7, v80
	v_lshl_add_u64 v[54:55], v[20:21], 0, v[60:61]
	s_nop 0
	v_addc_co_u32_e32 v87, vcc, 0, v81, vcc
	v_add_co_u32_e32 v84, vcc, s9, v80
	v_lshl_add_u64 v[58:59], v[20:21], 0, v[58:59]
	s_nop 0
	v_addc_co_u32_e32 v85, vcc, 0, v81, vcc
	v_add_co_u32_e32 v60, vcc, s7, v56
	s_add_i32 s4, s4, 4
	s_nop 0
	v_addc_co_u32_e32 v61, vcc, 0, v57, vcc
	v_add_co_u32_e32 v62, vcc, s9, v56
	s_cmp_eq_u32 s4, 16
	s_nop 0
	v_addc_co_u32_e32 v63, vcc, 0, v57, vcc
	s_waitcnt vmcnt(3)
	v_lshlrev_b32_e32 v98, 16, v64
	v_and_b32_e32 v99, 0xffff0000, v64
	v_lshlrev_b32_e32 v64, 16, v65
	v_and_b32_e32 v65, 0xffff0000, v65
	v_lshlrev_b32_e32 v100, 16, v66
	v_and_b32_e32 v101, 0xffff0000, v66
	v_lshlrev_b32_e32 v66, 16, v67
	s_waitcnt vmcnt(1)
	v_lshlrev_b32_e32 v105, 16, v72
	v_and_b32_e32 v107, 0xffff0000, v72
	v_lshlrev_b32_e32 v111, 16, v73
	v_and_b32_e32 v113, 0xffff0000, v73
	v_and_b32_e32 v67, 0xffff0000, v67
	v_lshlrev_b32_e32 v102, 16, v68
	v_and_b32_e32 v103, 0xffff0000, v68
	s_waitcnt vmcnt(0)
	v_lshlrev_b32_e32 v104, 16, v76
	v_and_b32_e32 v106, 0xffff0000, v76
	v_lshlrev_b32_e32 v108, 16, v69
	v_and_b32_e32 v109, 0xffff0000, v69
	v_lshlrev_b32_e32 v110, 16, v77
	v_and_b32_e32 v112, 0xffff0000, v77
	v_lshlrev_b32_e32 v76, 16, v70
	v_and_b32_e32 v77, 0xffff0000, v70
	v_lshlrev_b32_e32 v115, 16, v74
	v_and_b32_e32 v117, 0xffff0000, v74
	v_lshlrev_b32_e32 v70, 16, v71
	v_and_b32_e32 v71, 0xffff0000, v71
	v_lshlrev_b32_e32 v119, 16, v75
	v_and_b32_e32 v75, 0xffff0000, v75
	v_mul_f32_e32 v39, 0xbfb8aa3b, v105
	v_mul_f32_e32 v41, 0xbfb8aa3b, v107
	v_mul_f32_e32 v45, 0xbfb8aa3b, v111
	v_mul_f32_e32 v51, 0xbfb8aa3b, v113
	v_lshlrev_b32_e32 v114, 16, v78
	v_and_b32_e32 v116, 0xffff0000, v78
	v_lshlrev_b32_e32 v118, 16, v79
	v_and_b32_e32 v74, 0xffff0000, v79
	v_pk_mul_f32 v[68:69], v[98:99], v[102:103]
	v_pk_mul_f32 v[72:73], v[64:65], v[108:109]
	v_pk_mul_f32 v[76:77], v[100:101], v[76:77]
	v_mul_f32_e32 v53, 0xbfb8aa3b, v115
	v_mul_f32_e32 v64, 0xbfb8aa3b, v117
	v_pk_mul_f32 v[78:79], v[66:67], v[70:71]
	v_mul_f32_e32 v65, 0xbfb8aa3b, v119
	v_mul_f32_e32 v66, 0xbfb8aa3b, v75
	v_exp_f32_e32 v89, v39
	v_exp_f32_e32 v99, v41
	v_exp_f32_e32 v101, v45
	v_exp_f32_e32 v103, v51
	v_mov_b32_e32 v43, v68
	v_mov_b32_e32 v47, v69
	v_mov_b32_e32 v49, v73
	v_mov_b32_e32 v51, v77
	v_exp_f32_e32 v109, v53
	v_exp_f32_e32 v121, v64
	v_mov_b32_e32 v53, v79
	v_exp_f32_e32 v123, v65
	v_exp_f32_e32 v125, v66
	v_mov_b32_e32 v39, v72
	v_mov_b32_e32 v45, v76
	v_mov_b32_e32 v41, v78
	v_pk_mul_f32 v[64:65], v[22:23], v[42:43]
	v_pk_mul_f32 v[66:67], v[2:3], v[46:47]
	v_pk_mul_f32 v[128:129], v[4:5], v[48:49]
	v_pk_mul_f32 v[132:133], v[6:7], v[50:51]
	v_pk_mul_f32 v[136:137], v[8:9], v[52:53]
	v_pk_mul_f32 v[70:71], v[24:25], v[38:39]
	v_pk_mul_f32 v[130:131], v[26:27], v[44:45]
	v_pk_mul_f32 v[134:135], v[28:29], v[40:41]
	v_fma_f32 v32, v10, v32, v64
	v_fma_f32 v33, v11, v33, v66
	v_fma_f32 v31, v13, v31, v128
	v_fma_f32 v37, v15, v37, v132
	v_fma_f32 v35, v17, v35, v136
	v_fma_f32 v39, v12, v30, v70
	v_fma_f32 v41, v14, v36, v130
	v_fma_f32 v43, v16, v34, v134
	v_add_f32_e32 v30, v32, v65
	v_add_f32_e32 v32, v33, v67
	v_add_f32_e32 v36, v31, v129
	v_add_f32_e32 v66, v37, v133
	v_add_f32_e32 v128, v35, v137
	v_add_f32_e32 v31, 1.0, v89
	v_add_f32_e32 v33, 1.0, v99
	v_add_f32_e32 v35, 1.0, v101
	v_add_f32_e32 v37, 1.0, v103
	v_add_f32_e32 v34, v39, v71
	v_add_f32_e32 v64, v41, v131
	v_add_f32_e32 v70, v43, v135
	v_add_f32_e32 v39, 1.0, v109
	v_add_f32_e32 v41, 1.0, v121
	v_add_f32_e32 v43, 1.0, v123
	v_add_f32_e32 v45, 1.0, v125
	v_rcp_f32_e32 v31, v31
	v_rcp_f32_e32 v33, v33
	v_rcp_f32_e32 v35, v35
	v_rcp_f32_e32 v37, v37
	v_rcp_f32_e32 v65, v39
	v_rcp_f32_e32 v67, v41
	v_rcp_f32_e32 v71, v43
	v_rcp_f32_e32 v129, v45
	v_pk_mul_f32 v[30:31], v[30:31], v[104:105]
	v_pk_mul_f32 v[32:33], v[32:33], v[106:107]
	v_pk_mul_f32 v[34:35], v[34:35], v[110:111]
	v_pk_mul_f32 v[36:37], v[36:37], v[112:113]
	v_pk_mul_f32 v[64:65], v[64:65], v[114:115]
	v_pk_mul_f32 v[66:67], v[66:67], v[116:117]
	v_pk_mul_f32 v[70:71], v[70:71], v[118:119]
	v_pk_mul_f32 v[74:75], v[128:129], v[74:75]
	v_mul_f32_e32 v30, v30, v31
	v_mul_f32_e32 v31, v32, v33
	v_mul_f32_e32 v32, v34, v35
	v_mul_f32_e32 v33, v36, v37
	v_mul_f32_e32 v34, v64, v65
	v_mul_f32_e32 v35, v66, v67
	v_mul_f32_e32 v36, v70, v71
	v_mul_f32_e32 v37, v74, v75
	v_cvt_pk_bf16_f32 v30, v30, v31
	v_cvt_pk_bf16_f32 v31, v32, v33
	v_cvt_pk_bf16_f32 v32, v34, v35
	v_cvt_pk_bf16_f32 v33, v36, v37
	global_store_dwordx4 v[90:91], v[30:33], off nt
	global_load_dwordx4 v[30:33], v[92:93], off nt
	s_nop 0
	global_load_dwordx4 v[34:37], v[94:95], off nt
	global_load_dwordx4 v[64:67], v[96:97], off nt
	global_load_dwordx4 v[90:93], v[94:95], off offset:-4096 nt
	v_mov_b32_e32 v98, v68
	v_mov_b32_e32 v100, v69
	v_mov_b32_e32 v102, v72
	v_mov_b32_e32 v108, v73
	v_mov_b32_e32 v120, v76
	v_mov_b32_e32 v122, v77
	v_mov_b32_e32 v124, v78
	v_mov_b32_e32 v126, v79
	s_waitcnt vmcnt(3)
	v_lshlrev_b32_e32 v70, 16, v30
	v_and_b32_e32 v71, 0xffff0000, v30
	s_waitcnt vmcnt(2)
	v_lshlrev_b32_e32 v74, 16, v34
	v_and_b32_e32 v75, 0xffff0000, v34
	s_waitcnt vmcnt(1)
	v_lshlrev_b32_e32 v95, 16, v64
	v_and_b32_e32 v97, 0xffff0000, v64
	v_lshlrev_b32_e32 v30, 16, v31
	v_and_b32_e32 v31, 0xffff0000, v31
	v_lshlrev_b32_e32 v34, 16, v35
	v_and_b32_e32 v35, 0xffff0000, v35
	v_lshlrev_b32_e32 v105, 16, v65
	v_and_b32_e32 v107, 0xffff0000, v65
	s_waitcnt vmcnt(0)
	v_lshlrev_b32_e32 v94, 16, v90
	v_and_b32_e32 v96, 0xffff0000, v90
	v_lshlrev_b32_e32 v104, 16, v91
	v_and_b32_e32 v106, 0xffff0000, v91
	v_lshlrev_b32_e32 v90, 16, v32
	v_and_b32_e32 v91, 0xffff0000, v32
	v_lshlrev_b32_e32 v110, 16, v36
	v_and_b32_e32 v111, 0xffff0000, v36
	v_lshlrev_b32_e32 v113, 16, v66
	v_and_b32_e32 v115, 0xffff0000, v66
	v_lshlrev_b32_e32 v32, 16, v33
	v_and_b32_e32 v33, 0xffff0000, v33
	v_lshlrev_b32_e32 v36, 16, v37
	v_and_b32_e32 v37, 0xffff0000, v37
	v_lshlrev_b32_e32 v117, 16, v67
	v_and_b32_e32 v119, 0xffff0000, v67
	v_mul_f32_e32 v39, 0xbfb8aa3b, v95
	v_mul_f32_e32 v41, 0xbfb8aa3b, v97
	v_pk_mul_f32 v[66:67], v[30:31], v[34:35]
	v_mul_f32_e32 v30, 0xbfb8aa3b, v105
	v_mul_f32_e32 v31, 0xbfb8aa3b, v107
	v_pk_mul_f32 v[64:65], v[70:71], v[74:75]
	v_mul_f32_e32 v34, 0xbfb8aa3b, v113
	v_mul_f32_e32 v35, 0xbfb8aa3b, v115
	v_pk_mul_f32 v[74:75], v[32:33], v[36:37]
	v_mul_f32_e32 v32, 0xbfb8aa3b, v117
	v_mul_f32_e32 v33, 0xbfb8aa3b, v119
	v_exp_f32_e32 v39, v39
	v_exp_f32_e32 v41, v41
	v_exp_f32_e32 v43, v30
	v_exp_f32_e32 v45, v31
	v_mov_b32_e32 v99, v64
	v_mov_b32_e32 v101, v65
	v_mov_b32_e32 v103, v66
	v_mov_b32_e32 v109, v67
	v_exp_f32_e32 v47, v34
	v_exp_f32_e32 v49, v35
	v_exp_f32_e32 v51, v32
	v_exp_f32_e32 v53, v33
	v_pk_mul_f32 v[30:31], v[22:23], v[98:99]
	v_pk_mul_f32 v[32:33], v[2:3], v[100:101]
	v_pk_mul_f32 v[34:35], v[24:25], v[102:103]
	v_pk_mul_f32 v[36:37], v[4:5], v[108:109]
	v_fma_f32 v30, v10, v42, v30
	v_fma_f32 v32, v11, v46, v32
	v_fma_f32 v34, v12, v38, v34
	v_fma_f32 v36, v13, v48, v36
	v_add_f32_e32 v30, v30, v31
	v_add_f32_e32 v32, v32, v33
	v_add_f32_e32 v34, v34, v35
	v_add_f32_e32 v36, v36, v37
	v_add_f32_e32 v31, 1.0, v39
	v_add_f32_e32 v33, 1.0, v41
	v_add_f32_e32 v35, 1.0, v43
	v_add_f32_e32 v37, 1.0, v45
	v_pk_mul_f32 v[70:71], v[90:91], v[110:111]
	v_add_f32_e32 v39, 1.0, v47
	v_add_f32_e32 v41, 1.0, v49
	v_add_f32_e32 v43, 1.0, v51
	v_add_f32_e32 v45, 1.0, v53
	v_rcp_f32_e32 v31, v31
	v_rcp_f32_e32 v33, v33
	v_rcp_f32_e32 v35, v35
	v_rcp_f32_e32 v37, v37
	v_mov_b32_e32 v121, v70
	v_mov_b32_e32 v123, v71
	v_mov_b32_e32 v125, v74
	v_mov_b32_e32 v127, v75
	v_rcp_f32_e32 v39, v39
	v_rcp_f32_e32 v41, v41
	v_rcp_f32_e32 v43, v43
	v_rcp_f32_e32 v45, v45
	v_pk_mul_f32 v[98:99], v[26:27], v[120:121]
	v_pk_mul_f32 v[100:101], v[6:7], v[122:123]
	v_pk_mul_f32 v[102:103], v[28:29], v[124:125]
	v_pk_mul_f32 v[108:109], v[8:9], v[126:127]
	v_fma_f32 v38, v14, v44, v98
	v_fma_f32 v42, v15, v50, v100
	v_fma_f32 v44, v16, v40, v102
	v_fma_f32 v46, v17, v52, v108
	v_lshlrev_b32_e32 v112, 16, v92
	v_and_b32_e32 v114, 0xffff0000, v92
	v_lshlrev_b32_e32 v116, 16, v93
	v_and_b32_e32 v118, 0xffff0000, v93
	v_add_f32_e32 v38, v38, v99
	v_add_f32_e32 v40, v42, v101
	v_add_f32_e32 v42, v44, v103
	v_add_f32_e32 v44, v46, v109
	v_pk_mul_f32 v[30:31], v[30:31], v[94:95]
	v_pk_mul_f32 v[32:33], v[32:33], v[96:97]
	v_pk_mul_f32 v[34:35], v[34:35], v[104:105]
	v_pk_mul_f32 v[36:37], v[36:37], v[106:107]
	v_pk_mul_f32 v[38:39], v[38:39], v[112:113]
	v_pk_mul_f32 v[40:41], v[40:41], v[114:115]
	v_pk_mul_f32 v[42:43], v[42:43], v[116:117]
	v_pk_mul_f32 v[44:45], v[44:45], v[118:119]
	v_mul_f32_e32 v30, v30, v31
	v_mul_f32_e32 v31, v32, v33
	v_mul_f32_e32 v32, v34, v35
	v_mul_f32_e32 v33, v36, v37
	v_mul_f32_e32 v34, v38, v39
	v_mul_f32_e32 v35, v40, v41
	v_mul_f32_e32 v36, v42, v43
	v_mul_f32_e32 v37, v44, v45
	v_cvt_pk_bf16_f32 v30, v30, v31
	v_cvt_pk_bf16_f32 v31, v32, v33
	v_cvt_pk_bf16_f32 v32, v34, v35
	v_cvt_pk_bf16_f32 v33, v36, v37
	global_store_dwordx4 v[82:83], v[30:33], off nt
	global_load_dwordx4 v[30:33], v[80:81], off nt
	s_nop 0
	global_load_dwordx4 v[34:37], v[86:87], off nt
	global_load_dwordx4 v[38:41], v[84:85], off nt
	global_load_dwordx4 v[42:45], v[86:87], off offset:-4096 nt
	v_mov_b32_e32 v128, v67
	v_mov_b32_e32 v90, v64
	v_mov_b32_e32 v92, v65
	v_mov_b32_e32 v110, v66
	v_mov_b32_e32 v132, v71
	v_mov_b32_e32 v134, v74
	v_mov_b32_e32 v136, v75
	v_mov_b32_e32 v130, v70
	s_waitcnt vmcnt(3)
	v_lshlrev_b32_e32 v46, 16, v30
	v_and_b32_e32 v47, 0xffff0000, v30
	s_waitcnt vmcnt(2)
	v_lshlrev_b32_e32 v48, 16, v34
	v_and_b32_e32 v49, 0xffff0000, v34
	s_waitcnt vmcnt(1)
	v_lshlrev_b32_e32 v81, 16, v39
	v_and_b32_e32 v39, 0xffff0000, v39
	v_lshlrev_b32_e32 v99, 16, v41
	v_and_b32_e32 v41, 0xffff0000, v41
	v_lshlrev_b32_e32 v51, 16, v38
	s_waitcnt vmcnt(0)
	v_lshlrev_b32_e32 v50, 16, v42
	v_and_b32_e32 v53, 0xffff0000, v38
	v_and_b32_e32 v52, 0xffff0000, v42
	v_lshlrev_b32_e32 v30, 16, v31
	v_and_b32_e32 v31, 0xffff0000, v31
	v_lshlrev_b32_e32 v34, 16, v35
	v_and_b32_e32 v35, 0xffff0000, v35
	v_lshlrev_b32_e32 v80, 16, v43
	v_and_b32_e32 v38, 0xffff0000, v43
	v_lshlrev_b32_e32 v42, 16, v32
	v_and_b32_e32 v43, 0xffff0000, v32
	v_lshlrev_b32_e32 v82, 16, v36
	v_and_b32_e32 v83, 0xffff0000, v36
	v_lshlrev_b32_e32 v85, 16, v40
	v_and_b32_e32 v87, 0xffff0000, v40
	v_lshlrev_b32_e32 v94, 16, v33
	v_and_b32_e32 v95, 0xffff0000, v33
	v_lshlrev_b32_e32 v96, 16, v37
	v_and_b32_e32 v97, 0xffff0000, v37
	v_pk_mul_f32 v[32:33], v[46:47], v[48:49]
	v_mul_f32_e32 v47, 0xbfb8aa3b, v39
	v_mul_f32_e32 v49, 0xbfb8aa3b, v41
	v_lshlrev_b32_e32 v84, 16, v44
	v_and_b32_e32 v86, 0xffff0000, v44
	v_lshlrev_b32_e32 v98, 16, v45
	v_and_b32_e32 v40, 0xffff0000, v45
	v_mul_f32_e32 v44, 0xbfb8aa3b, v51
	v_mul_f32_e32 v45, 0xbfb8aa3b, v53
	v_pk_mul_f32 v[30:31], v[30:31], v[34:35]
	v_mul_f32_e32 v46, 0xbfb8aa3b, v81
	v_pk_mul_f32 v[36:37], v[42:43], v[82:83]
	v_mul_f32_e32 v42, 0xbfb8aa3b, v85
	v_mul_f32_e32 v43, 0xbfb8aa3b, v87
	v_pk_mul_f32 v[34:35], v[94:95], v[96:97]
	v_mul_f32_e32 v48, 0xbfb8aa3b, v99
	v_exp_f32_e32 v97, v47
	v_exp_f32_e32 v107, v49
	v_exp_f32_e32 v83, v44
	v_exp_f32_e32 v89, v45
	v_mov_b32_e32 v129, v31
	v_exp_f32_e32 v95, v46
	v_exp_f32_e32 v101, v42
	v_exp_f32_e32 v103, v43
	v_exp_f32_e32 v105, v48
	v_mov_b32_e32 v91, v32
	v_mov_b32_e32 v93, v33
	v_mov_b32_e32 v111, v30
	v_mov_b32_e32 v133, v37
	v_mov_b32_e32 v135, v34
	v_mov_b32_e32 v137, v35
	v_pk_mul_f32 v[48:49], v[4:5], v[128:129]
	v_mov_b32_e32 v131, v36
	v_pk_mul_f32 v[42:43], v[22:23], v[90:91]
	v_pk_mul_f32 v[44:45], v[2:3], v[92:93]
	v_pk_mul_f32 v[46:47], v[24:25], v[110:111]
	v_pk_mul_f32 v[92:93], v[6:7], v[132:133]
	v_pk_mul_f32 v[110:111], v[28:29], v[134:135]
	v_pk_mul_f32 v[112:113], v[8:9], v[136:137]
	v_fma_f32 v48, v13, v73, v48
	v_pk_mul_f32 v[90:91], v[26:27], v[130:131]
	v_fma_f32 v42, v10, v68, v42
	v_fma_f32 v44, v11, v69, v44
	v_fma_f32 v46, v12, v72, v46
	v_fma_f32 v69, v15, v77, v92
	v_fma_f32 v73, v16, v78, v110
	v_fma_f32 v77, v17, v79, v112
	v_add_f32_e32 v48, v48, v49
	v_add_f32_e32 v49, 1.0, v97
	v_add_f32_e32 v79, 1.0, v107
	v_fma_f32 v68, v14, v76, v90
	v_add_f32_e32 v42, v42, v43
	v_add_f32_e32 v44, v44, v45
	v_add_f32_e32 v46, v46, v47
	v_add_f32_e32 v72, v69, v93
	v_add_f32_e32 v76, v73, v111
	v_add_f32_e32 v78, v77, v113
	v_add_f32_e32 v43, 1.0, v83
	v_add_f32_e32 v45, 1.0, v89
	v_add_f32_e32 v47, 1.0, v95
	v_add_f32_e32 v69, 1.0, v101
	v_add_f32_e32 v73, 1.0, v103
	v_add_f32_e32 v77, 1.0, v105
	v_rcp_f32_e32 v49, v49
	v_rcp_f32_e32 v79, v79
	v_rcp_f32_e32 v43, v43
	v_rcp_f32_e32 v45, v45
	v_rcp_f32_e32 v47, v47
	v_rcp_f32_e32 v69, v69
	v_rcp_f32_e32 v73, v73
	v_rcp_f32_e32 v77, v77
	v_add_f32_e32 v68, v68, v91
	v_pk_mul_f32 v[38:39], v[48:49], v[38:39]
	v_pk_mul_f32 v[40:41], v[78:79], v[40:41]
	v_pk_mul_f32 v[42:43], v[42:43], v[50:51]
	v_pk_mul_f32 v[44:45], v[44:45], v[52:53]
	v_pk_mul_f32 v[46:47], v[46:47], v[80:81]
	v_pk_mul_f32 v[48:49], v[68:69], v[84:85]
	v_pk_mul_f32 v[50:51], v[72:73], v[86:87]
	v_pk_mul_f32 v[52:53], v[76:77], v[98:99]
	v_mul_f32_e32 v39, v38, v39
	v_mul_f32_e32 v41, v40, v41
	v_mul_f32_e32 v42, v42, v43
	v_mul_f32_e32 v43, v44, v45
	v_mul_f32_e32 v44, v46, v47
	v_mul_f32_e32 v45, v48, v49
	v_mul_f32_e32 v46, v50, v51
	v_mul_f32_e32 v47, v52, v53
	v_cvt_pk_bf16_f32 v38, v42, v43
	v_cvt_pk_bf16_f32 v39, v44, v39
	v_cvt_pk_bf16_f32 v40, v45, v46
	v_cvt_pk_bf16_f32 v41, v47, v41
	global_store_dwordx4 v[58:59], v[38:41], off nt
	global_load_dwordx4 v[38:41], v[56:57], off nt
	s_nop 0
	global_load_dwordx4 v[42:45], v[60:61], off nt
	global_load_dwordx4 v[46:49], v[62:63], off nt
	global_load_dwordx4 v[50:53], v[60:61], off offset:-4096 nt
	v_mov_b32_e32 v82, v32
	v_mov_b32_e32 v94, v33
	v_mov_b32_e32 v96, v30
	v_mov_b32_e32 v100, v31
	v_mov_b32_e32 v102, v36
	v_mov_b32_e32 v104, v37
	v_mov_b32_e32 v106, v34
	v_mov_b32_e32 v108, v35
	s_waitcnt vmcnt(3)
	v_lshlrev_b32_e32 v56, 16, v38
	v_and_b32_e32 v57, 0xffff0000, v38
	s_waitcnt vmcnt(1)
	v_lshlrev_b32_e32 v61, 16, v46
	s_waitcnt vmcnt(0)
	v_lshlrev_b32_e32 v60, 16, v50
	v_and_b32_e32 v63, 0xffff0000, v46
	v_and_b32_e32 v62, 0xffff0000, v50
	v_lshlrev_b32_e32 v73, 16, v47
	v_lshlrev_b32_e32 v72, 16, v51
	v_and_b32_e32 v77, 0xffff0000, v47
	v_and_b32_e32 v76, 0xffff0000, v51
	v_lshlrev_b32_e32 v46, 16, v40
	v_and_b32_e32 v47, 0xffff0000, v40
	v_lshlrev_b32_e32 v50, 16, v44
	v_and_b32_e32 v51, 0xffff0000, v44
	v_lshlrev_b32_e32 v79, 16, v48
	v_and_b32_e32 v81, 0xffff0000, v48
	v_lshlrev_b32_e32 v87, 16, v49
	v_and_b32_e32 v91, 0xffff0000, v49
	v_lshlrev_b32_e32 v58, 16, v42
	v_and_b32_e32 v59, 0xffff0000, v42
	v_lshlrev_b32_e32 v38, 16, v39
	v_and_b32_e32 v39, 0xffff0000, v39
	v_lshlrev_b32_e32 v68, 16, v43
	v_and_b32_e32 v69, 0xffff0000, v43
	v_lshlrev_b32_e32 v78, 16, v52
	v_and_b32_e32 v80, 0xffff0000, v52
	v_lshlrev_b32_e32 v84, 16, v45
	v_and_b32_e32 v85, 0xffff0000, v45
	v_lshlrev_b32_e32 v86, 16, v53
	v_and_b32_e32 v90, 0xffff0000, v53
	v_mul_f32_e32 v48, 0xbfb8aa3b, v61
	v_mul_f32_e32 v49, 0xbfb8aa3b, v63
	v_mul_f32_e32 v52, 0xbfb8aa3b, v73
	v_mul_f32_e32 v53, 0xbfb8aa3b, v77
	v_pk_mul_f32 v[44:45], v[46:47], v[50:51]
	v_mul_f32_e32 v46, 0xbfb8aa3b, v79
	v_mul_f32_e32 v47, 0xbfb8aa3b, v81
	v_mul_f32_e32 v50, 0xbfb8aa3b, v87
	v_mul_f32_e32 v51, 0xbfb8aa3b, v91
	v_lshlrev_b32_e32 v40, 16, v41
	v_and_b32_e32 v41, 0xffff0000, v41
	v_pk_mul_f32 v[42:43], v[56:57], v[58:59]
	v_pk_mul_f32 v[38:39], v[38:39], v[68:69]
	v_exp_f32_e32 v89, v48
	v_exp_f32_e32 v49, v49
	v_exp_f32_e32 v98, v52
	v_exp_f32_e32 v53, v53
	v_exp_f32_e32 v99, v46
	v_exp_f32_e32 v47, v47
	v_exp_f32_e32 v110, v50
	v_exp_f32_e32 v51, v51
	v_pk_mul_f32 v[40:41], v[40:41], v[84:85]
	v_mov_b32_e32 v83, v42
	v_mov_b32_e32 v95, v43
	v_mov_b32_e32 v97, v38
	v_mov_b32_e32 v101, v39
	v_mov_b32_e32 v103, v44
	v_mov_b32_e32 v105, v45
	v_mov_b32_e32 v107, v40
	v_mov_b32_e32 v109, v41
	v_pk_mul_f32 v[56:57], v[22:23], v[82:83]
	v_pk_mul_f32 v[58:59], v[2:3], v[94:95]
	v_pk_mul_f32 v[68:69], v[24:25], v[96:97]
	v_pk_mul_f32 v[82:83], v[4:5], v[100:101]
	v_mov_b32_e32 v46, v43
	v_mov_b32_e32 v48, v39
	v_mov_b32_e32 v50, v45
	v_mov_b32_e32 v52, v41
	v_pk_mul_f32 v[84:85], v[26:27], v[102:103]
	v_pk_mul_f32 v[92:93], v[6:7], v[104:105]
	v_pk_mul_f32 v[94:95], v[28:29], v[106:107]
	v_pk_mul_f32 v[96:97], v[8:9], v[108:109]
	v_fma_f32 v39, v10, v64, v56
	v_fma_f32 v41, v11, v65, v58
	v_fma_f32 v43, v12, v66, v68
	v_fma_f32 v45, v13, v67, v82
	v_fma_f32 v65, v14, v70, v84
	v_fma_f32 v67, v15, v71, v92
	v_fma_f32 v71, v16, v74, v94
	v_fma_f32 v75, v17, v75, v96
	v_add_f32_e32 v56, v39, v57
	v_add_f32_e32 v58, v41, v59
	v_add_f32_e32 v64, v43, v69
	v_add_f32_e32 v66, v45, v83
	v_add_f32_e32 v39, 1.0, v89
	v_add_f32_e32 v41, 1.0, v49
	v_add_f32_e32 v43, 1.0, v98
	v_add_f32_e32 v45, 1.0, v53
	v_add_f32_e32 v49, 1.0, v99
	v_add_f32_e32 v47, 1.0, v47
	v_add_f32_e32 v53, 1.0, v110
	v_add_f32_e32 v51, 1.0, v51
	v_add_f32_e32 v68, v65, v85
	v_add_f32_e32 v70, v67, v93
	v_add_f32_e32 v74, v71, v95
	v_add_f32_e32 v82, v75, v97
	v_rcp_f32_e32 v57, v39
	v_rcp_f32_e32 v59, v41
	v_rcp_f32_e32 v65, v43
	v_rcp_f32_e32 v67, v45
	v_rcp_f32_e32 v69, v49
	v_rcp_f32_e32 v71, v47
	v_rcp_f32_e32 v75, v53
	v_rcp_f32_e32 v83, v51
	v_pk_mul_f32 v[56:57], v[56:57], v[60:61]
	v_pk_mul_f32 v[58:59], v[58:59], v[62:63]
	v_pk_mul_f32 v[60:61], v[64:65], v[72:73]
	v_pk_mul_f32 v[62:63], v[66:67], v[76:77]
	v_pk_mul_f32 v[64:65], v[68:69], v[78:79]
	v_pk_mul_f32 v[66:67], v[70:71], v[80:81]
	v_pk_mul_f32 v[68:69], v[74:75], v[86:87]
	v_pk_mul_f32 v[70:71], v[82:83], v[90:91]
	v_mul_f32_e32 v39, v56, v57
	v_mul_f32_e32 v41, v58, v59
	v_mul_f32_e32 v43, v60, v61
	v_mul_f32_e32 v45, v62, v63
	v_mul_f32_e32 v47, v64, v65
	v_mul_f32_e32 v49, v66, v67
	v_mul_f32_e32 v51, v68, v69
	v_mul_f32_e32 v53, v70, v71
	v_cvt_pk_bf16_f32 v56, v39, v41
	v_cvt_pk_bf16_f32 v57, v43, v45
	v_cvt_pk_bf16_f32 v58, v47, v49
	v_cvt_pk_bf16_f32 v59, v51, v53
	global_store_dwordx4 v[54:55], v[56:59], off nt
	s_cbranch_scc0 .LBB0_446
	s_add_i32 s6, s6, s3
	s_cmpk_gt_i32 s6, 0x1ff
	v_add_u32_e32 v88, s8, v88
	s_cbranch_scc0 .LBB0_443

.LBB0_673:
	v_add_u32_e32 v54, s4, v88
	v_ashrrev_i32_e32 v55, 31, v54
	v_lshlrev_b64 v[62:63], 15, v[54:55]
	v_lshl_add_u64 v[62:63], v[18:19], 0, v[62:63]
	v_add_u32_e32 v56, 1, v54
	v_add_u32_e32 v58, 2, v54
	v_add_u32_e32 v60, 3, v54
	v_add_co_u32_e32 v84, vcc, s7, v62
	v_lshlrev_b64 v[54:55], 12, v[54:55]
	v_ashrrev_i32_e32 v57, 31, v56
	v_ashrrev_i32_e32 v59, 31, v58
	v_ashrrev_i32_e32 v61, 31, v60
	v_addc_co_u32_e32 v85, vcc, 0, v63, vcc
	v_lshl_add_u64 v[90:91], v[20:21], 0, v[54:55]
	v_lshlrev_b64 v[54:55], 15, v[56:57]
	v_lshlrev_b64 v[56:57], 12, v[56:57]
	v_lshlrev_b64 v[68:69], 15, v[58:59]
	v_lshlrev_b64 v[70:71], 15, v[60:61]
	global_load_dwordx4 v[64:67], v[62:63], off nt
	v_add_co_u32_e32 v62, vcc, s9, v62
	v_lshl_add_u64 v[82:83], v[20:21], 0, v[56:57]
	s_nop 0
	v_addc_co_u32_e32 v63, vcc, 0, v63, vcc
	v_lshl_add_u64 v[80:81], v[18:19], 0, v[68:69]
	v_lshl_add_u64 v[56:57], v[18:19], 0, v[70:71]
	global_load_dwordx4 v[68:71], v[84:85], off nt
	global_load_dwordx4 v[72:75], v[62:63], off nt
	global_load_dwordx4 v[76:79], v[84:85], off offset:-4096 nt
	v_lshl_add_u64 v[92:93], v[18:19], 0, v[54:55]
	v_add_co_u32_e32 v94, vcc, s7, v92
	v_lshlrev_b64 v[60:61], 12, v[60:61]
	s_nop 0
	v_addc_co_u32_e32 v95, vcc, 0, v93, vcc
	v_add_co_u32_e32 v96, vcc, s9, v92
	v_lshlrev_b64 v[58:59], 12, v[58:59]
	s_nop 0
	v_addc_co_u32_e32 v97, vcc, 0, v93, vcc
	v_add_co_u32_e32 v84, vcc, s7, v80
	v_lshl_add_u64 v[54:55], v[20:21], 0, v[60:61]
	s_nop 0
	v_addc_co_u32_e32 v85, vcc, 0, v81, vcc
	v_add_co_u32_e32 v86, vcc, s9, v80
	v_lshl_add_u64 v[58:59], v[20:21], 0, v[58:59]
	s_nop 0
	v_addc_co_u32_e32 v87, vcc, 0, v81, vcc
	v_add_co_u32_e32 v60, vcc, s7, v56
	s_add_i32 s4, s4, 4
	s_nop 0
	v_addc_co_u32_e32 v61, vcc, 0, v57, vcc
	v_add_co_u32_e32 v62, vcc, s9, v56
	s_cmp_eq_u32 s4, 16
	s_nop 0
	v_addc_co_u32_e32 v63, vcc, 0, v57, vcc
	s_waitcnt vmcnt(3)
	v_lshlrev_b32_e32 v98, 16, v64
	v_and_b32_e32 v99, 0xffff0000, v64
	v_lshlrev_b32_e32 v64, 16, v65
	v_and_b32_e32 v65, 0xffff0000, v65
	v_lshlrev_b32_e32 v100, 16, v66
	v_and_b32_e32 v101, 0xffff0000, v66
	v_lshlrev_b32_e32 v66, 16, v67
	s_waitcnt vmcnt(1)
	v_lshlrev_b32_e32 v105, 16, v72
	v_and_b32_e32 v107, 0xffff0000, v72
	v_lshlrev_b32_e32 v111, 16, v73
	v_and_b32_e32 v113, 0xffff0000, v73
	v_and_b32_e32 v67, 0xffff0000, v67
	v_lshlrev_b32_e32 v102, 16, v68
	v_and_b32_e32 v103, 0xffff0000, v68
	s_waitcnt vmcnt(0)
	v_lshlrev_b32_e32 v104, 16, v76
	v_and_b32_e32 v106, 0xffff0000, v76
	v_lshlrev_b32_e32 v108, 16, v69
	v_and_b32_e32 v109, 0xffff0000, v69
	v_lshlrev_b32_e32 v110, 16, v77
	v_and_b32_e32 v112, 0xffff0000, v77
	v_lshlrev_b32_e32 v76, 16, v70
	v_and_b32_e32 v77, 0xffff0000, v70
	v_lshlrev_b32_e32 v115, 16, v74
	v_and_b32_e32 v117, 0xffff0000, v74
	v_lshlrev_b32_e32 v70, 16, v71
	v_and_b32_e32 v71, 0xffff0000, v71
	v_lshlrev_b32_e32 v119, 16, v75
	v_and_b32_e32 v75, 0xffff0000, v75
	v_mul_f32_e32 v39, 0xbfb8aa3b, v105
	v_mul_f32_e32 v41, 0xbfb8aa3b, v107
	v_mul_f32_e32 v45, 0xbfb8aa3b, v111
	v_mul_f32_e32 v51, 0xbfb8aa3b, v113
	v_lshlrev_b32_e32 v114, 16, v78
	v_and_b32_e32 v116, 0xffff0000, v78
	v_lshlrev_b32_e32 v118, 16, v79
	v_and_b32_e32 v74, 0xffff0000, v79
	v_pk_mul_f32 v[68:69], v[98:99], v[102:103]
	v_pk_mul_f32 v[72:73], v[64:65], v[108:109]
	v_pk_mul_f32 v[76:77], v[100:101], v[76:77]
	v_mul_f32_e32 v53, 0xbfb8aa3b, v115
	v_mul_f32_e32 v64, 0xbfb8aa3b, v117
	v_pk_mul_f32 v[78:79], v[66:67], v[70:71]
	v_mul_f32_e32 v65, 0xbfb8aa3b, v119
	v_mul_f32_e32 v66, 0xbfb8aa3b, v75
	v_exp_f32_e32 v89, v39
	v_exp_f32_e32 v99, v41
	v_exp_f32_e32 v101, v45
	v_exp_f32_e32 v103, v51
	v_mov_b32_e32 v43, v68
	v_mov_b32_e32 v47, v69
	v_mov_b32_e32 v49, v73
	v_mov_b32_e32 v51, v77
	v_exp_f32_e32 v109, v53
	v_exp_f32_e32 v121, v64
	v_mov_b32_e32 v53, v79
	v_exp_f32_e32 v123, v65
	v_exp_f32_e32 v125, v66
	v_mov_b32_e32 v39, v72
	v_mov_b32_e32 v45, v76
	v_mov_b32_e32 v41, v78
	v_pk_mul_f32 v[64:65], v[22:23], v[42:43]
	v_pk_mul_f32 v[66:67], v[2:3], v[46:47]
	v_pk_mul_f32 v[128:129], v[4:5], v[48:49]
	v_pk_mul_f32 v[132:133], v[6:7], v[50:51]
	v_pk_mul_f32 v[136:137], v[8:9], v[52:53]
	v_pk_mul_f32 v[70:71], v[24:25], v[38:39]
	v_pk_mul_f32 v[130:131], v[26:27], v[44:45]
	v_pk_mul_f32 v[134:135], v[28:29], v[40:41]
	v_fma_f32 v32, v10, v32, v64
	v_fma_f32 v33, v11, v33, v66
	v_fma_f32 v31, v13, v31, v128
	v_fma_f32 v37, v15, v37, v132
	v_fma_f32 v35, v17, v35, v136
	v_fma_f32 v39, v12, v30, v70
	v_fma_f32 v41, v14, v36, v130
	v_fma_f32 v43, v16, v34, v134
	v_add_f32_e32 v30, v32, v65
	v_add_f32_e32 v32, v33, v67
	v_add_f32_e32 v36, v31, v129
	v_add_f32_e32 v66, v37, v133
	v_add_f32_e32 v128, v35, v137
	v_add_f32_e32 v31, 1.0, v89
	v_add_f32_e32 v33, 1.0, v99
	v_add_f32_e32 v35, 1.0, v101
	v_add_f32_e32 v37, 1.0, v103
	v_add_f32_e32 v34, v39, v71
	v_add_f32_e32 v64, v41, v131
	v_add_f32_e32 v70, v43, v135
	v_add_f32_e32 v39, 1.0, v109
	v_add_f32_e32 v41, 1.0, v121
	v_add_f32_e32 v43, 1.0, v123
	v_add_f32_e32 v45, 1.0, v125
	v_rcp_f32_e32 v31, v31
	v_rcp_f32_e32 v33, v33
	v_rcp_f32_e32 v35, v35
	v_rcp_f32_e32 v37, v37
	v_rcp_f32_e32 v65, v39
	v_rcp_f32_e32 v67, v41
	v_rcp_f32_e32 v71, v43
	v_rcp_f32_e32 v129, v45
	v_pk_mul_f32 v[30:31], v[30:31], v[104:105]
	v_pk_mul_f32 v[32:33], v[32:33], v[106:107]
	v_pk_mul_f32 v[34:35], v[34:35], v[110:111]
	v_pk_mul_f32 v[36:37], v[36:37], v[112:113]
	v_pk_mul_f32 v[64:65], v[64:65], v[114:115]
	v_pk_mul_f32 v[66:67], v[66:67], v[116:117]
	v_pk_mul_f32 v[70:71], v[70:71], v[118:119]
	v_pk_mul_f32 v[74:75], v[128:129], v[74:75]
	v_mul_f32_e32 v30, v30, v31
	v_mul_f32_e32 v31, v32, v33
	v_mul_f32_e32 v32, v34, v35
	v_mul_f32_e32 v33, v36, v37
	v_mul_f32_e32 v34, v64, v65
	v_mul_f32_e32 v35, v66, v67
	v_mul_f32_e32 v36, v70, v71
	v_mul_f32_e32 v37, v74, v75
	v_cvt_pk_bf16_f32 v30, v30, v31
	v_cvt_pk_bf16_f32 v31, v32, v33
	v_cvt_pk_bf16_f32 v32, v34, v35
	v_cvt_pk_bf16_f32 v33, v36, v37
	global_store_dwordx4 v[90:91], v[30:33], off nt
	global_load_dwordx4 v[30:33], v[92:93], off nt
	s_nop 0
	global_load_dwordx4 v[34:37], v[94:95], off nt
	global_load_dwordx4 v[64:67], v[96:97], off nt
	global_load_dwordx4 v[90:93], v[94:95], off offset:-4096 nt
	v_mov_b32_e32 v98, v68
	v_mov_b32_e32 v100, v69
	v_mov_b32_e32 v102, v72
	v_mov_b32_e32 v108, v73
	v_mov_b32_e32 v120, v76
	v_mov_b32_e32 v122, v77
	v_mov_b32_e32 v124, v78
	v_mov_b32_e32 v126, v79
	s_waitcnt vmcnt(3)
	v_lshlrev_b32_e32 v70, 16, v30
	v_and_b32_e32 v71, 0xffff0000, v30
	s_waitcnt vmcnt(2)
	v_lshlrev_b32_e32 v74, 16, v34
	v_and_b32_e32 v75, 0xffff0000, v34
	s_waitcnt vmcnt(1)
	v_lshlrev_b32_e32 v95, 16, v64
	v_and_b32_e32 v97, 0xffff0000, v64
	v_lshlrev_b32_e32 v30, 16, v31
	v_and_b32_e32 v31, 0xffff0000, v31
	v_lshlrev_b32_e32 v34, 16, v35
	v_and_b32_e32 v35, 0xffff0000, v35
	v_lshlrev_b32_e32 v105, 16, v65
	v_and_b32_e32 v107, 0xffff0000, v65
	s_waitcnt vmcnt(0)
	v_lshlrev_b32_e32 v94, 16, v90
	v_and_b32_e32 v96, 0xffff0000, v90
	v_lshlrev_b32_e32 v104, 16, v91
	v_and_b32_e32 v106, 0xffff0000, v91
	v_lshlrev_b32_e32 v90, 16, v32
	v_and_b32_e32 v91, 0xffff0000, v32
	v_lshlrev_b32_e32 v110, 16, v36
	v_and_b32_e32 v111, 0xffff0000, v36
	v_lshlrev_b32_e32 v113, 16, v66
	v_and_b32_e32 v115, 0xffff0000, v66
	v_lshlrev_b32_e32 v32, 16, v33
	v_and_b32_e32 v33, 0xffff0000, v33
	v_lshlrev_b32_e32 v36, 16, v37
	v_and_b32_e32 v37, 0xffff0000, v37
	v_lshlrev_b32_e32 v117, 16, v67
	v_and_b32_e32 v119, 0xffff0000, v67
	v_mul_f32_e32 v39, 0xbfb8aa3b, v95
	v_mul_f32_e32 v41, 0xbfb8aa3b, v97
	v_pk_mul_f32 v[66:67], v[30:31], v[34:35]
	v_mul_f32_e32 v30, 0xbfb8aa3b, v105
	v_mul_f32_e32 v31, 0xbfb8aa3b, v107
	v_pk_mul_f32 v[64:65], v[70:71], v[74:75]
	v_mul_f32_e32 v34, 0xbfb8aa3b, v113
	v_mul_f32_e32 v35, 0xbfb8aa3b, v115
	v_pk_mul_f32 v[74:75], v[32:33], v[36:37]
	v_mul_f32_e32 v32, 0xbfb8aa3b, v117
	v_mul_f32_e32 v33, 0xbfb8aa3b, v119
	v_exp_f32_e32 v39, v39
	v_exp_f32_e32 v41, v41
	v_exp_f32_e32 v43, v30
	v_exp_f32_e32 v45, v31
	v_mov_b32_e32 v99, v64
	v_mov_b32_e32 v101, v65
	v_mov_b32_e32 v103, v66
	v_mov_b32_e32 v109, v67
	v_exp_f32_e32 v47, v34
	v_exp_f32_e32 v49, v35
	v_exp_f32_e32 v51, v32
	v_exp_f32_e32 v53, v33
	v_pk_mul_f32 v[30:31], v[22:23], v[98:99]
	v_pk_mul_f32 v[32:33], v[2:3], v[100:101]
	v_pk_mul_f32 v[34:35], v[24:25], v[102:103]
	v_pk_mul_f32 v[36:37], v[4:5], v[108:109]
	v_fma_f32 v30, v10, v42, v30
	v_fma_f32 v32, v11, v46, v32
	v_fma_f32 v34, v12, v38, v34
	v_fma_f32 v36, v13, v48, v36
	v_add_f32_e32 v30, v30, v31
	v_add_f32_e32 v32, v32, v33
	v_add_f32_e32 v34, v34, v35
	v_add_f32_e32 v36, v36, v37
	v_add_f32_e32 v31, 1.0, v39
	v_add_f32_e32 v33, 1.0, v41
	v_add_f32_e32 v35, 1.0, v43
	v_add_f32_e32 v37, 1.0, v45
	v_pk_mul_f32 v[70:71], v[90:91], v[110:111]
	v_add_f32_e32 v39, 1.0, v47
	v_add_f32_e32 v41, 1.0, v49
	v_add_f32_e32 v43, 1.0, v51
	v_add_f32_e32 v45, 1.0, v53
	v_rcp_f32_e32 v31, v31
	v_rcp_f32_e32 v33, v33
	v_rcp_f32_e32 v35, v35
	v_rcp_f32_e32 v37, v37
	v_mov_b32_e32 v121, v70
	v_mov_b32_e32 v123, v71
	v_mov_b32_e32 v125, v74
	v_mov_b32_e32 v127, v75
	v_rcp_f32_e32 v39, v39
	v_rcp_f32_e32 v41, v41
	v_rcp_f32_e32 v43, v43
	v_rcp_f32_e32 v45, v45
	v_pk_mul_f32 v[98:99], v[26:27], v[120:121]
	v_pk_mul_f32 v[100:101], v[6:7], v[122:123]
	v_pk_mul_f32 v[102:103], v[28:29], v[124:125]
	v_pk_mul_f32 v[108:109], v[8:9], v[126:127]
	v_fma_f32 v38, v14, v44, v98
	v_fma_f32 v42, v15, v50, v100
	v_fma_f32 v44, v16, v40, v102
	v_fma_f32 v46, v17, v52, v108
	v_lshlrev_b32_e32 v112, 16, v92
	v_and_b32_e32 v114, 0xffff0000, v92
	v_lshlrev_b32_e32 v116, 16, v93
	v_and_b32_e32 v118, 0xffff0000, v93
	v_add_f32_e32 v38, v38, v99
	v_add_f32_e32 v40, v42, v101
	v_add_f32_e32 v42, v44, v103
	v_add_f32_e32 v44, v46, v109
	v_pk_mul_f32 v[30:31], v[30:31], v[94:95]
	v_pk_mul_f32 v[32:33], v[32:33], v[96:97]
	v_pk_mul_f32 v[34:35], v[34:35], v[104:105]
	v_pk_mul_f32 v[36:37], v[36:37], v[106:107]
	v_pk_mul_f32 v[38:39], v[38:39], v[112:113]
	v_pk_mul_f32 v[40:41], v[40:41], v[114:115]
	v_pk_mul_f32 v[42:43], v[42:43], v[116:117]
	v_pk_mul_f32 v[44:45], v[44:45], v[118:119]
	v_mul_f32_e32 v30, v30, v31
	v_mul_f32_e32 v31, v32, v33
	v_mul_f32_e32 v32, v34, v35
	v_mul_f32_e32 v33, v36, v37
	v_mul_f32_e32 v34, v38, v39
	v_mul_f32_e32 v35, v40, v41
	v_mul_f32_e32 v36, v42, v43
	v_mul_f32_e32 v37, v44, v45
	v_cvt_pk_bf16_f32 v30, v30, v31
	v_cvt_pk_bf16_f32 v31, v32, v33
	v_cvt_pk_bf16_f32 v32, v34, v35
	v_cvt_pk_bf16_f32 v33, v36, v37
	global_store_dwordx4 v[82:83], v[30:33], off nt
	global_load_dwordx4 v[30:33], v[80:81], off nt
	s_nop 0
	global_load_dwordx4 v[34:37], v[84:85], off nt
	global_load_dwordx4 v[38:41], v[86:87], off nt
	global_load_dwordx4 v[42:45], v[84:85], off offset:-4096 nt
	v_mov_b32_e32 v128, v67
	v_mov_b32_e32 v90, v64
	v_mov_b32_e32 v92, v65
	v_mov_b32_e32 v110, v66
	v_mov_b32_e32 v132, v71
	v_mov_b32_e32 v134, v74
	v_mov_b32_e32 v136, v75
	v_mov_b32_e32 v130, v70
	s_waitcnt vmcnt(3)
	v_lshlrev_b32_e32 v46, 16, v30
	v_and_b32_e32 v47, 0xffff0000, v30
	s_waitcnt vmcnt(2)
	v_lshlrev_b32_e32 v48, 16, v34
	v_and_b32_e32 v49, 0xffff0000, v34
	s_waitcnt vmcnt(1)
	v_lshlrev_b32_e32 v81, 16, v39
	v_and_b32_e32 v39, 0xffff0000, v39
	v_lshlrev_b32_e32 v99, 16, v41
	v_and_b32_e32 v41, 0xffff0000, v41
	v_lshlrev_b32_e32 v51, 16, v38
	s_waitcnt vmcnt(0)
	v_lshlrev_b32_e32 v50, 16, v42
	v_and_b32_e32 v53, 0xffff0000, v38
	v_and_b32_e32 v52, 0xffff0000, v42
	v_lshlrev_b32_e32 v30, 16, v31
	v_and_b32_e32 v31, 0xffff0000, v31
	v_lshlrev_b32_e32 v34, 16, v35
	v_and_b32_e32 v35, 0xffff0000, v35
	v_lshlrev_b32_e32 v80, 16, v43
	v_and_b32_e32 v38, 0xffff0000, v43
	v_lshlrev_b32_e32 v42, 16, v32
	v_and_b32_e32 v43, 0xffff0000, v32
	v_lshlrev_b32_e32 v82, 16, v36
	v_and_b32_e32 v83, 0xffff0000, v36
	v_lshlrev_b32_e32 v85, 16, v40
	v_and_b32_e32 v87, 0xffff0000, v40
	v_lshlrev_b32_e32 v94, 16, v33
	v_and_b32_e32 v95, 0xffff0000, v33
	v_lshlrev_b32_e32 v96, 16, v37
	v_and_b32_e32 v97, 0xffff0000, v37
	v_pk_mul_f32 v[32:33], v[46:47], v[48:49]
	v_mul_f32_e32 v47, 0xbfb8aa3b, v39
	v_mul_f32_e32 v49, 0xbfb8aa3b, v41
	v_lshlrev_b32_e32 v84, 16, v44
	v_and_b32_e32 v86, 0xffff0000, v44
	v_lshlrev_b32_e32 v98, 16, v45
	v_and_b32_e32 v40, 0xffff0000, v45
	v_mul_f32_e32 v44, 0xbfb8aa3b, v51
	v_mul_f32_e32 v45, 0xbfb8aa3b, v53
	v_pk_mul_f32 v[30:31], v[30:31], v[34:35]
	v_mul_f32_e32 v46, 0xbfb8aa3b, v81
	v_pk_mul_f32 v[36:37], v[42:43], v[82:83]
	v_mul_f32_e32 v42, 0xbfb8aa3b, v85
	v_mul_f32_e32 v43, 0xbfb8aa3b, v87
	v_pk_mul_f32 v[34:35], v[94:95], v[96:97]
	v_mul_f32_e32 v48, 0xbfb8aa3b, v99
	v_exp_f32_e32 v97, v47
	v_exp_f32_e32 v107, v49
	v_exp_f32_e32 v83, v44
	v_exp_f32_e32 v89, v45
	v_mov_b32_e32 v129, v31
	v_exp_f32_e32 v95, v46
	v_exp_f32_e32 v101, v42
	v_exp_f32_e32 v103, v43
	v_exp_f32_e32 v105, v48
	v_mov_b32_e32 v91, v32
	v_mov_b32_e32 v93, v33
	v_mov_b32_e32 v111, v30
	v_mov_b32_e32 v133, v37
	v_mov_b32_e32 v135, v34
	v_mov_b32_e32 v137, v35
	v_pk_mul_f32 v[48:49], v[4:5], v[128:129]
	v_mov_b32_e32 v131, v36
	v_pk_mul_f32 v[42:43], v[22:23], v[90:91]
	v_pk_mul_f32 v[44:45], v[2:3], v[92:93]
	v_pk_mul_f32 v[46:47], v[24:25], v[110:111]
	v_pk_mul_f32 v[92:93], v[6:7], v[132:133]
	v_pk_mul_f32 v[110:111], v[28:29], v[134:135]
	v_pk_mul_f32 v[112:113], v[8:9], v[136:137]
	v_fma_f32 v48, v13, v73, v48
	v_pk_mul_f32 v[90:91], v[26:27], v[130:131]
	v_fma_f32 v42, v10, v68, v42
	v_fma_f32 v44, v11, v69, v44
	v_fma_f32 v46, v12, v72, v46
	v_fma_f32 v69, v15, v77, v92
	v_fma_f32 v73, v16, v78, v110
	v_fma_f32 v77, v17, v79, v112
	v_add_f32_e32 v48, v48, v49
	v_add_f32_e32 v49, 1.0, v97
	v_add_f32_e32 v79, 1.0, v107
	v_fma_f32 v68, v14, v76, v90
	v_add_f32_e32 v42, v42, v43
	v_add_f32_e32 v44, v44, v45
	v_add_f32_e32 v46, v46, v47
	v_add_f32_e32 v72, v69, v93
	v_add_f32_e32 v76, v73, v111
	v_add_f32_e32 v78, v77, v113
	v_add_f32_e32 v43, 1.0, v83
	v_add_f32_e32 v45, 1.0, v89
	v_add_f32_e32 v47, 1.0, v95
	v_add_f32_e32 v69, 1.0, v101
	v_add_f32_e32 v73, 1.0, v103
	v_add_f32_e32 v77, 1.0, v105
	v_rcp_f32_e32 v49, v49
	v_rcp_f32_e32 v79, v79
	v_rcp_f32_e32 v43, v43
	v_rcp_f32_e32 v45, v45
	v_rcp_f32_e32 v47, v47
	v_rcp_f32_e32 v69, v69
	v_rcp_f32_e32 v73, v73
	v_rcp_f32_e32 v77, v77
	v_add_f32_e32 v68, v68, v91
	v_pk_mul_f32 v[38:39], v[48:49], v[38:39]
	v_pk_mul_f32 v[40:41], v[78:79], v[40:41]
	v_pk_mul_f32 v[42:43], v[42:43], v[50:51]
	v_pk_mul_f32 v[44:45], v[44:45], v[52:53]
	v_pk_mul_f32 v[46:47], v[46:47], v[80:81]
	v_pk_mul_f32 v[48:49], v[68:69], v[84:85]
	v_pk_mul_f32 v[50:51], v[72:73], v[86:87]
	v_pk_mul_f32 v[52:53], v[76:77], v[98:99]
	v_mul_f32_e32 v39, v38, v39
	v_mul_f32_e32 v41, v40, v41
	v_mul_f32_e32 v42, v42, v43
	v_mul_f32_e32 v43, v44, v45
	v_mul_f32_e32 v44, v46, v47
	v_mul_f32_e32 v45, v48, v49
	v_mul_f32_e32 v46, v50, v51
	v_mul_f32_e32 v47, v52, v53
	v_cvt_pk_bf16_f32 v38, v42, v43
	v_cvt_pk_bf16_f32 v39, v44, v39
	v_cvt_pk_bf16_f32 v40, v45, v46
	v_cvt_pk_bf16_f32 v41, v47, v41
	global_store_dwordx4 v[58:59], v[38:41], off nt
	global_load_dwordx4 v[38:41], v[56:57], off nt
	s_nop 0
	global_load_dwordx4 v[42:45], v[60:61], off nt
	global_load_dwordx4 v[46:49], v[62:63], off nt
	global_load_dwordx4 v[50:53], v[60:61], off offset:-4096 nt
	v_mov_b32_e32 v82, v32
	v_mov_b32_e32 v94, v33
	v_mov_b32_e32 v96, v30
	v_mov_b32_e32 v100, v31
	v_mov_b32_e32 v102, v36
	v_mov_b32_e32 v104, v37
	v_mov_b32_e32 v106, v34
	v_mov_b32_e32 v108, v35
	s_waitcnt vmcnt(3)
	v_lshlrev_b32_e32 v56, 16, v38
	v_and_b32_e32 v57, 0xffff0000, v38
	s_waitcnt vmcnt(1)
	v_lshlrev_b32_e32 v61, 16, v46
	s_waitcnt vmcnt(0)
	v_lshlrev_b32_e32 v60, 16, v50
	v_and_b32_e32 v63, 0xffff0000, v46
	v_and_b32_e32 v62, 0xffff0000, v50
	v_lshlrev_b32_e32 v73, 16, v47
	v_lshlrev_b32_e32 v72, 16, v51
	v_and_b32_e32 v77, 0xffff0000, v47
	v_and_b32_e32 v76, 0xffff0000, v51
	v_lshlrev_b32_e32 v46, 16, v40
	v_and_b32_e32 v47, 0xffff0000, v40
	v_lshlrev_b32_e32 v50, 16, v44
	v_and_b32_e32 v51, 0xffff0000, v44
	v_lshlrev_b32_e32 v79, 16, v48
	v_and_b32_e32 v81, 0xffff0000, v48
	v_lshlrev_b32_e32 v87, 16, v49
	v_and_b32_e32 v91, 0xffff0000, v49
	v_lshlrev_b32_e32 v58, 16, v42
	v_and_b32_e32 v59, 0xffff0000, v42
	v_lshlrev_b32_e32 v38, 16, v39
	v_and_b32_e32 v39, 0xffff0000, v39
	v_lshlrev_b32_e32 v68, 16, v43
	v_and_b32_e32 v69, 0xffff0000, v43
	v_lshlrev_b32_e32 v78, 16, v52
	v_and_b32_e32 v80, 0xffff0000, v52
	v_lshlrev_b32_e32 v84, 16, v45
	v_and_b32_e32 v85, 0xffff0000, v45
	v_lshlrev_b32_e32 v86, 16, v53
	v_and_b32_e32 v90, 0xffff0000, v53
	v_mul_f32_e32 v48, 0xbfb8aa3b, v61
	v_mul_f32_e32 v49, 0xbfb8aa3b, v63
	v_mul_f32_e32 v52, 0xbfb8aa3b, v73
	v_mul_f32_e32 v53, 0xbfb8aa3b, v77
	v_pk_mul_f32 v[44:45], v[46:47], v[50:51]
	v_mul_f32_e32 v46, 0xbfb8aa3b, v79
	v_mul_f32_e32 v47, 0xbfb8aa3b, v81
	v_mul_f32_e32 v50, 0xbfb8aa3b, v87
	v_mul_f32_e32 v51, 0xbfb8aa3b, v91
	v_lshlrev_b32_e32 v40, 16, v41
	v_and_b32_e32 v41, 0xffff0000, v41
	v_pk_mul_f32 v[42:43], v[56:57], v[58:59]
	v_pk_mul_f32 v[38:39], v[38:39], v[68:69]
	v_exp_f32_e32 v89, v48
	v_exp_f32_e32 v49, v49
	v_exp_f32_e32 v98, v52
	v_exp_f32_e32 v53, v53
	v_exp_f32_e32 v99, v46
	v_exp_f32_e32 v47, v47
	v_exp_f32_e32 v110, v50
	v_exp_f32_e32 v51, v51
	v_pk_mul_f32 v[40:41], v[40:41], v[84:85]
	v_mov_b32_e32 v83, v42
	v_mov_b32_e32 v95, v43
	v_mov_b32_e32 v97, v38
	v_mov_b32_e32 v101, v39
	v_mov_b32_e32 v103, v44
	v_mov_b32_e32 v105, v45
	v_mov_b32_e32 v107, v40
	v_mov_b32_e32 v109, v41
	v_pk_mul_f32 v[56:57], v[22:23], v[82:83]
	v_pk_mul_f32 v[58:59], v[2:3], v[94:95]
	v_pk_mul_f32 v[68:69], v[24:25], v[96:97]
	v_pk_mul_f32 v[82:83], v[4:5], v[100:101]
	v_mov_b32_e32 v46, v43
	v_mov_b32_e32 v48, v39
	v_mov_b32_e32 v50, v45
	v_mov_b32_e32 v52, v41
	v_pk_mul_f32 v[84:85], v[26:27], v[102:103]
	v_pk_mul_f32 v[92:93], v[6:7], v[104:105]
	v_pk_mul_f32 v[94:95], v[28:29], v[106:107]
	v_pk_mul_f32 v[96:97], v[8:9], v[108:109]
	v_fma_f32 v39, v10, v64, v56
	v_fma_f32 v41, v11, v65, v58
	v_fma_f32 v43, v12, v66, v68
	v_fma_f32 v45, v13, v67, v82
	v_fma_f32 v65, v14, v70, v84
	v_fma_f32 v67, v15, v71, v92
	v_fma_f32 v71, v16, v74, v94
	v_fma_f32 v75, v17, v75, v96
	v_add_f32_e32 v56, v39, v57
	v_add_f32_e32 v58, v41, v59
	v_add_f32_e32 v64, v43, v69
	v_add_f32_e32 v66, v45, v83
	v_add_f32_e32 v39, 1.0, v89
	v_add_f32_e32 v41, 1.0, v49
	v_add_f32_e32 v43, 1.0, v98
	v_add_f32_e32 v45, 1.0, v53
	v_add_f32_e32 v49, 1.0, v99
	v_add_f32_e32 v47, 1.0, v47
	v_add_f32_e32 v53, 1.0, v110
	v_add_f32_e32 v51, 1.0, v51
	v_add_f32_e32 v68, v65, v85
	v_add_f32_e32 v70, v67, v93
	v_add_f32_e32 v74, v71, v95
	v_add_f32_e32 v82, v75, v97
	v_rcp_f32_e32 v57, v39
	v_rcp_f32_e32 v59, v41
	v_rcp_f32_e32 v65, v43
	v_rcp_f32_e32 v67, v45
	v_rcp_f32_e32 v69, v49
	v_rcp_f32_e32 v71, v47
	v_rcp_f32_e32 v75, v53
	v_rcp_f32_e32 v83, v51
	v_pk_mul_f32 v[56:57], v[56:57], v[60:61]
	v_pk_mul_f32 v[58:59], v[58:59], v[62:63]
	v_pk_mul_f32 v[60:61], v[64:65], v[72:73]
	v_pk_mul_f32 v[62:63], v[66:67], v[76:77]
	v_pk_mul_f32 v[64:65], v[68:69], v[78:79]
	v_pk_mul_f32 v[66:67], v[70:71], v[80:81]
	v_pk_mul_f32 v[68:69], v[74:75], v[86:87]
	v_pk_mul_f32 v[70:71], v[82:83], v[90:91]
	v_mul_f32_e32 v39, v56, v57
	v_mul_f32_e32 v41, v58, v59
	v_mul_f32_e32 v43, v60, v61
	v_mul_f32_e32 v45, v62, v63
	v_mul_f32_e32 v47, v64, v65
	v_mul_f32_e32 v49, v66, v67
	v_mul_f32_e32 v51, v68, v69
	v_mul_f32_e32 v53, v70, v71
	v_cvt_pk_bf16_f32 v56, v39, v41
	v_cvt_pk_bf16_f32 v57, v43, v45
	v_cvt_pk_bf16_f32 v58, v47, v49
	v_cvt_pk_bf16_f32 v59, v51, v53
	global_store_dwordx4 v[54:55], v[56:59], off nt
	s_cbranch_scc0 .LBB0_673
	s_add_i32 s6, s6, s3
	s_cmpk_gt_i32 s6, 0x1ff
	v_add_u32_e32 v88, s8, v88
	s_cbranch_scc0 .LBB0_670
